# baseline (speedup 1.0000x reference)
; #define SLOAD(i, k0) do { sr_[i].vs0 = *reinterpret_cast<const bf16x8*>(&Vh[(size_t)((k0) + sr) * LDQ + sc]); sr_[i].vs1 = *reinterpret_cast<const bf16x8*>(&Vh[(size_t)((k0) + 32 + sr) * LDQ + sc]); \
;     sr_[i].ks0 = *reinterpret_cast<const bf16x8*>(&Kh[(size_t)((k0) + sr) * LDQ + sc]); sr_[i].ks1 = *reinterpret_cast<const bf16x8*>(&Kh[(size_t)((k0) + 32 + sr) * LDQ + sc]); } while (0)
; #define SWRITE(b, i) do { *(bf16x8*)((char*)V_lds + (b) * SHM_V + vst0) = sr_[i].vs0;          \
;     *(bf16x8*)((char*)V_lds + (b) * SHM_V + vst1) = sr_[i].vs1; int kc = sc * 2;               \
;     *(bf16x8*)((char*)K_lds + (b) * SHM_K + KSWZ(sr, kc)) = sr_[i].ks0;                       \
;     *(bf16x8*)((char*)K_lds + (b) * SHM_K + KSWZ(32 + sr, kc)) = sr_[i].ks1; } while (0)
; template <bool SAFE>
; __device__ __forceinline__ void diff_core(const bf16* __restrict__ Kh, const bf16* __restrict__ Vh, const int NT, const bf16x8* qr, char* lds,
;                                           const int wid, const int lane_unused, f32x16* o, f32x16& lacc, float& l_reg) {
;     ...
;   const int kw0 = KSWZ(sr, sc * 2), kw1 = KSWZ(32 + sr, sc * 2);
;   SLOAD(0, 0); asm volatile("s_waitcnt vmcnt(0)" ::: "memory"); SWRITE(0, 0);
;   SLOAD(0, 64); asm volatile("s_waitcnt vmcnt(0)" ::: "memory"); SWRITE(1, 0); __syncthreads();
;   SLOAD(0, 128);
;   FIXUP(K_lds, true);
;   int bc = 1, bp = 0, bn = 2;
.LBB0_104:
	s_or_b64 exec, exec, s[4:5]
	v_and_b32_e32 v200, 63, v0
	v_lshlrev_b32_e32 v0, 4, v2
	v_and_b32_e32 v0, 0xc0, v0
	v_and_or_b32 v0, v1, 24, v0
	v_and_b32_e32 v2, 32, v4
	v_and_b32_e32 v1, 0x100, v1
	s_waitcnt lgkmcnt(0)
	v_add_u32_e32 v9, s62, v3
	v_or3_b32 v8, v0, v2, v1
	ds_read_b128 v[0:3], v9 offset:192
	ds_read_b128 v[4:7], v9 offset:224
	ds_read_b128 v[50:53], v9 offset:128
	ds_read_b128 v[54:57], v9 offset:160
	v_sub_f32_e32 v16, v16, v48
	v_sub_f32_e32 v17, v17, v48
	v_sub_f32_e32 v18, v18, v48
	v_sub_f32_e32 v19, v19, v48
	v_sub_f32_e32 v20, v20, v48
	v_sub_f32_e32 v21, v21, v48
	v_sub_f32_e32 v22, v22, v48
	v_sub_f32_e32 v23, v23, v48
	v_sub_f32_e32 v24, v24, v48
	v_sub_f32_e32 v25, v25, v48
	v_sub_f32_e32 v26, v26, v48
	v_sub_f32_e32 v27, v27, v48
	v_sub_f32_e32 v28, v28, v48
	v_sub_f32_e32 v29, v29, v48
	v_sub_f32_e32 v30, v30, v48
	v_sub_f32_e32 v31, v31, v48
	v_sub_f32_e32 v32, v32, v48
	v_sub_f32_e32 v33, v33, v48
	v_sub_f32_e32 v34, v34, v48
	v_sub_f32_e32 v35, v35, v48
	v_sub_f32_e32 v36, v36, v48
	v_sub_f32_e32 v37, v37, v48
	v_sub_f32_e32 v38, v38, v48
	v_sub_f32_e32 v39, v39, v48
	v_sub_f32_e32 v40, v40, v48
	v_sub_f32_e32 v41, v41, v48
	v_sub_f32_e32 v42, v42, v48
	v_sub_f32_e32 v43, v43, v48
	v_sub_f32_e32 v44, v44, v48
	v_sub_f32_e32 v45, v45, v48
	v_sub_f32_e32 v46, v46, v48
	v_sub_f32_e32 v47, v47, v48
	v_exp_f32_e32 v16, v16
	v_exp_f32_e32 v17, v17
	v_exp_f32_e32 v18, v18
	v_exp_f32_e32 v19, v19
	v_exp_f32_e32 v20, v20
	v_exp_f32_e32 v21, v21
	v_exp_f32_e32 v22, v22
	v_exp_f32_e32 v23, v23
	v_exp_f32_e32 v24, v24
	v_exp_f32_e32 v25, v25
	v_exp_f32_e32 v26, v26
	v_exp_f32_e32 v27, v27
	v_exp_f32_e32 v28, v28
	v_exp_f32_e32 v29, v29
	v_exp_f32_e32 v30, v30
	v_exp_f32_e32 v31, v31
	v_exp_f32_e32 v32, v32
	v_exp_f32_e32 v33, v33
	v_exp_f32_e32 v34, v34
	v_exp_f32_e32 v35, v35
	v_exp_f32_e32 v36, v36
	v_exp_f32_e32 v37, v37
	v_exp_f32_e32 v38, v38
	v_exp_f32_e32 v39, v39
	v_exp_f32_e32 v40, v40
	v_exp_f32_e32 v41, v41
	v_exp_f32_e32 v42, v42
	v_exp_f32_e32 v43, v43
	v_exp_f32_e32 v44, v44
	v_exp_f32_e32 v45, v45
	v_exp_f32_e32 v46, v46
	v_exp_f32_e32 v47, v47
	s_lshl_b32 s12, s8, 7
	s_cmp_lg_u32 0, -1
	s_cselect_b32 s5, 0, 0
	s_waitcnt lgkmcnt(2)
	v_pk_mul_f32 v[14:15], v[6:7], 0 op_sel_hi:[1,0]
	v_xor_b32_e32 v80, 0x80000000, v48
	v_add_u32_e32 v211, s5, v8
	v_pk_mul_f32 v[10:11], v[2:3], 0 op_sel_hi:[1,0]
	s_waitcnt lgkmcnt(0)
	v_pk_mul_f32 v[6:7], v[56:57], 0 op_sel_hi:[1,0]
	v_pk_mul_f32 v[2:3], v[52:53], 0 op_sel_hi:[1,0]
	v_pk_mul_f32 v[12:13], v[4:5], 0 op_sel_hi:[1,0]
	v_pk_mul_f32 v[8:9], v[0:1], 0 op_sel_hi:[1,0]
	v_pk_mul_f32 v[4:5], v[54:55], 0 op_sel_hi:[1,0]
	v_pk_mul_f32 v[0:1], v[50:51], 0 op_sel_hi:[1,0]
	v_cvt_pk_bf16_f32 v160, v16, v17
	v_cvt_pk_bf16_f32 v161, v18, v19
	v_cvt_pk_bf16_f32 v182, v20, v21
	v_cvt_pk_bf16_f32 v183, v22, v23
	v_cvt_pk_bf16_f32 v170, v24, v25
	v_cvt_pk_bf16_f32 v171, v26, v27
	v_cvt_pk_bf16_f32 v186, v28, v29
	v_cvt_pk_bf16_f32 v187, v30, v31
	v_cvt_pk_bf16_f32 v180, v32, v33
	v_cvt_pk_bf16_f32 v181, v34, v35
	v_cvt_pk_bf16_f32 v178, v36, v37
	v_cvt_pk_bf16_f32 v179, v38, v39
	v_cvt_pk_bf16_f32 v188, v40, v41
	v_cvt_pk_bf16_f32 v189, v42, v43
	v_cvt_pk_bf16_f32 v174, v44, v45
	v_cvt_pk_bf16_f32 v175, v46, v47
	v_mov_b32_e32 v64, 0
	v_mov_b64_e32 v[46:47], v[14:15]
	v_mov_b64_e32 v[62:63], v[14:15]
	v_mov_b64_e32 v[30:31], v[14:15]
	v_mov_b32_e32 v81, v80
	v_mov_b32_e32 v82, v80
	v_mov_b32_e32 v83, v80
	v_mov_b32_e32 v84, v80
	v_mov_b32_e32 v85, v80
	v_mov_b32_e32 v86, v80
	v_mov_b32_e32 v87, v80
	v_mov_b32_e32 v88, v80
	v_mov_b32_e32 v89, v80
	v_mov_b32_e32 v90, v80
	v_mov_b32_e32 v91, v80
	v_mov_b32_e32 v92, v80
	v_mov_b32_e32 v93, v80
	v_mov_b32_e32 v94, v80
	v_mov_b32_e32 v95, v80
	s_mov_b32 s4, 0
	s_mov_b32 s5, 1
	v_lshl_add_u64 v[190:191], s[10:11], 0, v[194:195]
	v_mad_u32_u24 v247, v201, s80, v194
	s_add_i32 s93, s92, -1
	s_mov_b32 s9, 2
	v_mov_b64_e32 v[44:45], v[12:13]
	v_mov_b64_e32 v[42:43], v[10:11]
	v_mov_b64_e32 v[40:41], v[8:9]
	v_mov_b64_e32 v[38:39], v[6:7]
	v_mov_b64_e32 v[36:37], v[4:5]
	v_mov_b64_e32 v[34:35], v[2:3]
	v_mov_b64_e32 v[32:33], v[0:1]
	v_mov_b64_e32 v[60:61], v[12:13]
	v_mov_b64_e32 v[58:59], v[10:11]
	v_mov_b64_e32 v[56:57], v[8:9]
	v_mov_b64_e32 v[54:55], v[6:7]
	v_mov_b64_e32 v[52:53], v[4:5]
	v_mov_b64_e32 v[50:51], v[2:3]
	v_mov_b64_e32 v[48:49], v[0:1]
	v_mov_b64_e32 v[28:29], v[12:13]
	v_mov_b64_e32 v[26:27], v[10:11]
	v_mov_b64_e32 v[24:25], v[8:9]
	v_mov_b64_e32 v[22:23], v[6:7]
	v_mov_b64_e32 v[20:21], v[4:5]
	v_mov_b64_e32 v[18:19], v[2:3]
	v_mov_b64_e32 v[16:17], v[0:1]
	s_mov_b32 s6, 1
	v_mov_b32_e32 v65, v64
	v_mov_b32_e32 v66, v64
	v_mov_b32_e32 v67, v64
	v_mov_b32_e32 v68, v64
	v_mov_b32_e32 v69, v64
	v_mov_b32_e32 v70, v64
	v_mov_b32_e32 v71, v64
	v_mov_b32_e32 v72, v64
	v_mov_b32_e32 v73, v64
	v_mov_b32_e32 v74, v64
	v_mov_b32_e32 v75, v64
	v_mov_b32_e32 v76, v64
	v_mov_b32_e32 v77, v64
	v_mov_b32_e32 v78, v64
	v_mov_b32_e32 v79, v64
	s_lshl_b32 s98, s6, 14
	v_add_u32_e32 v100, s98, v207
; template <int KS, bool SAFE> __device__ __forceinline__ void fused_ks(f32x16* o, f32x16& lacc, int vb, const VFrag& cur, VFrag& nxt, f32x16& p0, f32x16& p1, float& ps, ...
;   if constexpr (KS < 3) { vfrag_issue<KS + 1>(nxt, vb); asm volatile("s_waitcnt lgkmcnt(8)" ::: "memory"); }
;   else asm volatile("s_waitcnt lgkmcnt(0)" ::: "memory");
;   const bf16x8 pa = (KS == 0) ? pa0 : (KS == 1) ? pa1 : (KS == 2) ? pa2 : pa3;
;   SBAR();
;   o[0] = MFMA32(pa, PKV(cur.l0, cur.h0), o[0]); SBAR(); sm1_chunk<KS * 4 + 0>(p0, p1); if constexpr (KS > 0) SM2_UNIT(2 * KS - 1); SBAR();
;   o[1] = MFMA32(pa, PKV(cur.l1, cur.h1), o[1]); SBAR(); sm1_chunk<KS * 4 + 1>(p0, p1);
;   if (dow) {
;     if constexpr (KS == 0) { asm volatile("s_waitcnt vmcnt(0)" ::: "memory"); *reinterpret_cast<bf16x8*>(sd.k0) = st.ks0; }
;     else if constexpr (KS == 1) *reinterpret_cast<bf16x8*>(sd.k1) = st.ks1;
;     else if constexpr (KS == 2) *reinterpret_cast<bf16x8*>(sd.v0) = st.vs0;
;     else *reinterpret_cast<bf16x8*>(sd.v1) = st.vs1;
;   }
;   SBAR();
;   o[2] = MFMA32(pa, PKV(cur.l2, cur.h2), o[2]); SBAR(); sm1_chunk<KS * 4 + 2>(p0, p1); SM2_UNIT(2 * KS); SBAR();
;   o[3] = MFMA32(pa, PKV(cur.l3, cur.h3), o[3]); SBAR(); sm1_chunk<KS * 4 + 3>(p0, p1); SBAR();
;   if constexpr (!SAFE) { lacc = MFMA32(pa, ones, lacc); SBAR(); }
; }
; template <bool SAFE> ...
;   bf16x8 kb[8];
; #pragma unroll
;   for (int d0 = 0; d0 < 4; ++d0) { const int cb = (cb0 + d0 * 16 + hi * 8) * 2;
;     kb[2 * d0] = *reinterpret_cast<const bf16x8*>((const char*)Ks + KSWZ(r32, cb));
;     kb[2 * d0 + 1] = *reinterpret_cast<const bf16x8*>((const char*)Ks + KSWZ(32 + r32, cb)); }
;   VFrag fa, fb;
;   vfrag_issue<0>(fa, vb);
;   p0 = MFMA32(kb[0], qr[0], cinit); p1 = MFMA32(kb[1], qr[0], cinit);
; #pragma unroll
;   for (int d0 = 1; d0 < 4; ++d0) { p0 = MFMA32(kb[2 * d0], qr[d0], p0); p1 = MFMA32(kb[2 * d0 + 1], qr[d0], p1); }
;   SBAR();
;   unsigned a0, a1, b0, b1; ps = 0.f;
;   fused_ks<0, SAFE>(o, lacc, vb, fa, fb, p0, p1, ps, a0, a1, b0, b1, pa0, pa1, pa2, pa3, st, sd, dow, ones);
;   fused_ks<1, SAFE>(o, lacc, vb, fb, fa, p0, p1, ps, a0, a1, b0, b1, pa0, pa1, pa2, pa3, st, sd, dow, ones);
;   fused_ks<2, SAFE>(o, lacc, vb, fa, fb, p0, p1, ps, a0, a1, b0, b1, pa0, pa1, pa2, pa3, st, sd, dow, ones);
;   fused_ks<3, SAFE>(o, lacc, vb, fb, fa, p0, p1, ps, a0, a1, b0, b1, pa0, pa1, pa2, pa3, st, sd, dow, ones);
.LBB0_105:
	ds_read_b128 v[96:99], v100 offset:49152
	ds_read_b128 v[212:215], v100 offset:57344
	s_lshl_b32 s7, s6, 14
	s_add_i32 s66, s7, 0
	s_add_i32 s98, s5, 2
	s_min_i32 s98, s98, s93
	s_mul_i32 s98, s98, 0x60000
	s_add_u32 s98, s10, s98
	s_addc_u32 s99, s11, 0
	s_add_u32 s100, s98, 0x30000
	s_addc_u32 s101, s99, 0
	v_add_u32_e32 v172, s66, v208
	v_add_u32_e32 v173, s66, v209
	v_mov_b32_e32 v176, v180
	s_waitcnt lgkmcnt(1)
	v_mfma_f32_32x32x16_bf16 v[112:127], v[96:99], v[132:135], v[80:95]
	v_mov_b32_e32 v180, v160
	v_add_u32_e32 v160, s66, v210
	v_lshl_add_u32 v194, s4, 14, v211
	s_mov_b32 s8, s9
	s_lshl_b32 s9, s9, 14
	s_add_i32 s9, s9, 0
	v_mov_b32_e32 v184, v170
	s_waitcnt lgkmcnt(0)
	v_mfma_f32_32x32x16_bf16 v[96:111], v[212:215], v[132:135], v[80:95]
	ds_read_b128 v[212:215], v172 offset:49152
	ds_read_b128 v[216:219], v172 offset:57344
	v_mov_b32_e32 v177, v181
	v_mov_b32_e32 v172, v188
	v_mov_b32_e32 v181, v161
	v_add_u32_e32 v188, s9, v205
	v_add_u32_e32 v161, s9, v203
	v_add_u32_e32 v170, s9, v204
	s_waitcnt lgkmcnt(1)
	v_mfma_f32_32x32x16_bf16 v[112:127], v[212:215], v[136:139], v[112:127]
	ds_read_b128 v[212:215], v173 offset:49152
	v_mov_b32_e32 v185, v171
	s_waitcnt lgkmcnt(1)
	v_mfma_f32_32x32x16_bf16 v[96:111], v[216:219], v[136:139], v[96:111]
	ds_read_b128 v[216:219], v173 offset:57344
	v_mov_b32_e32 v173, v189
	v_add_u32_e32 v189, s9, v206
	s_waitcnt lgkmcnt(1)
	v_mfma_f32_32x32x16_bf16 v[112:127], v[212:215], v[140:143], v[112:127]
	ds_read_b128 v[212:215], v160 offset:49152
	s_waitcnt lgkmcnt(1)
	v_mfma_f32_32x32x16_bf16 v[96:111], v[216:219], v[140:143], v[96:111]
	ds_read_b128 v[216:219], v160 offset:57344
	ds_read_b64_tr_b16 v[220:221], v194 offset:0
	ds_read_b64_tr_b16 v[222:223], v194 offset:0x800
	s_waitcnt lgkmcnt(1)
	v_mfma_f32_32x32x16_bf16 v[112:127], v[212:215], v[144:147], v[112:127]
	ds_read_b64_tr_b16 v[212:213], v194 offset:0x200
	ds_read_b64_tr_b16 v[214:215], v194 offset:0xa00
	ds_read_b64_tr_b16 v[224:225], v194 offset:0x400
	ds_read_b64_tr_b16 v[226:227], v194 offset:0xc00
	ds_read_b64_tr_b16 v[228:229], v194 offset:0x600
	ds_read_b64_tr_b16 v[230:231], v194 offset:0xe00
	s_waitcnt lgkmcnt(0)
	v_mfma_f32_32x32x16_bf16 v[96:111], v[216:219], v[144:147], v[96:111]
	ds_read_b64_tr_b16 v[216:217], v194 offset:0x1000
	ds_read_b64_tr_b16 v[218:219], v194 offset:0x1800
	ds_read_b64_tr_b16 v[232:233], v194 offset:0x1200
	ds_read_b64_tr_b16 v[234:235], v194 offset:0x1a00
	ds_read_b64_tr_b16 v[236:237], v194 offset:0x1400
	ds_read_b64_tr_b16 v[238:239], v194 offset:0x1c00
	ds_read_b64_tr_b16 v[240:241], v194 offset:0x1600
	ds_read_b64_tr_b16 v[242:243], v194 offset:0x1e00
	s_waitcnt lgkmcnt(8)
	v_mfma_f32_32x32x16_bf16 v[48:63], v[180:183], v[220:223], v[48:63]
	s_nop 0
	v_exp_f32_e32 v112, v112
	v_exp_f32_e32 v113, v113
	v_mfma_f32_32x32x16_bf16 v[32:47], v[180:183], v[212:215], v[32:47]
	v_exp_f32_e32 v114, v114
	v_exp_f32_e32 v115, v115
	s_waitcnt vmcnt(3)
	ds_write_b128 v161, v[166:169] offset:49152
	global_load_dwordx4 v[166:169], v247, s[98:99] offset:1024
	v_mfma_f32_32x32x16_bf16 v[0:15], v[180:183], v[224:227], v[0:15]
	v_exp_f32_e32 v171, v116
	v_cvt_pk_bf16_f32 v160, v112, v113
	v_cvt_pk_bf16_f32 v161, v114, v115
	v_exp_f32_e32 v220, v117
	v_mfma_f32_32x32x16_bf16 v[16:31], v[180:183], v[228:231], v[16:31]
	v_exp_f32_e32 v221, v118
	v_exp_f32_e32 v222, v119
	v_mfma_f32_16x16x32_bf16 v[64:67], v[180:183], v[148:151], v[64:67]
	ds_read_b64_tr_b16 v[112:113], v194 offset:0x2000
	ds_read_b64_tr_b16 v[114:115], v194 offset:0x2800
	ds_read_b64_tr_b16 v[116:117], v194 offset:0x2200
	ds_read_b64_tr_b16 v[118:119], v194 offset:0x2a00
	ds_read_b64_tr_b16 v[248:249], v194 offset:0x2400
	ds_read_b64_tr_b16 v[250:251], v194 offset:0x2c00
	ds_read_b64_tr_b16 v[212:213], v194 offset:0x2600
	ds_read_b64_tr_b16 v[214:215], v194 offset:0x2e00
	s_waitcnt lgkmcnt(8)
	v_mfma_f32_32x32x16_bf16 v[48:63], v[184:187], v[216:219], v[48:63]
	v_cvt_pk_bf16_f32 v182, v171, v220
	v_cvt_pk_bf16_f32 v183, v221, v222
	v_exp_f32_e32 v120, v120
	v_exp_f32_e32 v121, v121
	v_mfma_f32_32x32x16_bf16 v[32:47], v[184:187], v[232:235], v[32:47]
	v_exp_f32_e32 v122, v122
	v_exp_f32_e32 v123, v123
	s_waitcnt vmcnt(3)
	ds_write_b128 v170, v[162:165] offset:49152
	global_load_dwordx4 v[162:165], v247, s[100:101] offset:1024
	v_mfma_f32_32x32x16_bf16 v[0:15], v[184:187], v[236:239], v[0:15]
	v_exp_f32_e32 v180, v124
	v_exp_f32_e32 v181, v125
	v_cvt_pk_bf16_f32 v170, v120, v121
	v_cvt_pk_bf16_f32 v171, v122, v123
	v_mfma_f32_32x32x16_bf16 v[16:31], v[184:187], v[240:243], v[16:31]
	v_exp_f32_e32 v220, v126
	v_exp_f32_e32 v221, v127
	v_mfma_f32_16x16x32_bf16 v[64:67], v[184:187], v[148:151], v[64:67]
	ds_read_b64_tr_b16 v[120:121], v194 offset:0x3000
	ds_read_b64_tr_b16 v[122:123], v194 offset:0x3800
	ds_read_b64_tr_b16 v[124:125], v194 offset:0x3200
	ds_read_b64_tr_b16 v[126:127], v194 offset:0x3a00
	ds_read_b64_tr_b16 v[252:253], v194 offset:0x3400
	ds_read_b64_tr_b16 v[254:255], v194 offset:0x3c00
	ds_read_b64_tr_b16 v[216:217], v194 offset:0x3600
	ds_read_b64_tr_b16 v[218:219], v194 offset:0x3e00
	s_waitcnt lgkmcnt(8)
	v_mfma_f32_32x32x16_bf16 v[48:63], v[176:179], v[112:115], v[48:63]
	v_cvt_pk_bf16_f32 v186, v180, v181
	v_cvt_pk_bf16_f32 v187, v220, v221
	v_exp_f32_e32 v96, v96
	v_exp_f32_e32 v97, v97
	v_mfma_f32_32x32x16_bf16 v[32:47], v[176:179], v[116:119], v[32:47]
	v_exp_f32_e32 v98, v98
	v_exp_f32_e32 v99, v99
	s_waitcnt vmcnt(3)
	ds_write_b128 v188, v[156:159]
	global_load_dwordx4 v[156:159], v247, s[98:99] offset:2048
	v_mfma_f32_32x32x16_bf16 v[0:15], v[176:179], v[248:251], v[0:15]
	v_cvt_pk_bf16_f32 v180, v96, v97
	v_cvt_pk_bf16_f32 v181, v98, v99
	v_exp_f32_e32 v100, v100
	v_exp_f32_e32 v101, v101
	v_mfma_f32_32x32x16_bf16 v[16:31], v[176:179], v[212:215], v[16:31]
	v_exp_f32_e32 v96, v102
	v_exp_f32_e32 v97, v103
	v_mfma_f32_16x16x32_bf16 v[64:67], v[176:179], v[148:151], v[64:67]
	s_waitcnt lgkmcnt(0)
	v_mfma_f32_32x32x16_bf16 v[48:63], v[172:175], v[120:123], v[48:63]
	v_cvt_pk_bf16_f32 v178, v100, v101
	v_cvt_pk_bf16_f32 v179, v96, v97
	v_exp_f32_e32 v98, v104
	v_exp_f32_e32 v99, v105
	v_mfma_f32_32x32x16_bf16 v[32:47], v[172:175], v[124:127], v[32:47]
	v_exp_f32_e32 v96, v106
	v_exp_f32_e32 v97, v107
	s_waitcnt vmcnt(3)
	ds_write_b128 v189, v[152:155]
	global_load_dwordx4 v[152:155], v247, s[100:101] offset:2048
	v_mfma_f32_32x32x16_bf16 v[0:15], v[172:175], v[252:255], v[0:15]
	v_cvt_pk_bf16_f32 v188, v98, v99
	v_cvt_pk_bf16_f32 v189, v96, v97
	v_exp_f32_e32 v100, v108
	v_exp_f32_e32 v101, v109
	v_mfma_f32_32x32x16_bf16 v[16:31], v[172:175], v[216:219], v[16:31]
	v_exp_f32_e32 v96, v110
	v_exp_f32_e32 v97, v111
	v_mfma_f32_16x16x32_bf16 v[64:67], v[172:175], v[148:151], v[64:67]
	v_cvt_pk_bf16_f32 v174, v100, v101
	v_cvt_pk_bf16_f32 v175, v96, v97
	s_add_i32 s5, s5, 1
	s_mov_b32 s9, s4
	s_mov_b32 s4, s6
	s_lshl_b32 s98, s8, 14
	v_add_u32_e32 v100, s98, v207
	s_cmp_lg_u32 s92, s5
	s_mov_b32 s6, s8
	s_waitcnt lgkmcnt(0)
	s_barrier
; #define SBAR() __builtin_amdgcn_sched_barrier(0)
; #define MFMA32(a, b, c) __builtin_amdgcn_mfma_f32_32x32x16_bf16(a, b, c, 0, 0, 0)
; #define SLOAD(i, k0) do { sr_[i].vs0 = *reinterpret_cast<const bf16x8*>(&Vh[(size_t)((k0) + sr) * LDQ + sc]); sr_[i].vs1 = *reinterpret_cast<const bf16x8*>(&Vh[(size_t)((k0) + 32 + sr) * LDQ + sc]); \
;     sr_[i].ks0 = *reinterpret_cast<const bf16x8*>(&Kh[(size_t)((k0) + sr) * LDQ + sc]); sr_[i].ks1 = *reinterpret_cast<const bf16x8*>(&Kh[(size_t)((k0) + 32 + sr) * LDQ + sc]); } while (0)
; template <bool SAFE>
; __device__ __forceinline__ void diff_core(const bf16* __restrict__ Kh, const bf16* __restrict__ Vh, const int NT, const bf16x8* qr, char* lds,
;                                           const int wid, const int lane_unused, f32x16* o, f32x16& lacc, float& l_reg) {
;     ...
;   for (int j = 1; j < NT; ++j) {
;     const bool dow = true;
;     const bf16* Kc = (const bf16*)((const char*)K_lds + bc * SHM_K);
;     StgDst sd;
;     sd.v0 = (char*)V_lds + bn * SHM_V + vst0; sd.v1 = (char*)V_lds + bn * SHM_V + vst1;
;     sd.k0 = (char*)K_lds + bn * SHM_K + kw0;  sd.k1 = (char*)K_lds + bn * SHM_K + kw1;
;     tile_step<SAFE>(o, lacc, Kc, vb0 + bp * SHM_V, qr, rk, hi, cb0, p0, p1, cinit, ps, pa0, pa1, pa2, pa3, sr_[0], sd, dow, ones);
;     SLOAD(0, min(j + 2, NT - 1) * 64);
;     SBAR();
;     if constexpr (SAFE) FIXUP(Kc, false);
;     asm volatile("s_waitcnt lgkmcnt(0)" ::: "memory"); __builtin_amdgcn_s_barrier(); asm volatile("" ::: "memory");
;     const int t_ = bp; bp = bc; bc = bn; bn = t_;
;   }
;   pv_d0(o, vb0 + bp * SHM_V, pa0, pa1, pa2, pa3);
;   if constexpr (!SAFE) {
;     lacc = MFMA32(pa0, ones, lacc); lacc = MFMA32(pa1, ones, lacc); lacc = MFMA32(pa2, ones, lacc); lacc = MFMA32(pa3, ones, lacc); }
; __device__ __forceinline__ void diff_attn_item(const bf16* __restrict__ qkv, bf16* __restrict__ mix, const float* __restrict__ dg,
;                                int tok0  , int key0  , int seq, int head, float lam, float oscale, const int W) {
;     ...
;     bool bad = (FORCE_SAFE != 0);
; #pragma unroll
;     for (int r = 0; r < 16; ++r) bad = bad || !(lacc[r] < 1.0e30f);
;     if (lane == 0) flag_l[wid] = __any(bad) ? 1 : 0;
	s_cbranch_scc1 .LBB0_105
	s_waitcnt vmcnt(0)
	v_add_u32_e32 v168, s7, v211
	ds_read_b64_tr_b16 v[80:81], v168 offset:0
	ds_read_b64_tr_b16 v[82:83], v168 offset:0x800
	ds_read_b64_tr_b16 v[84:85], v168 offset:0x1000
	ds_read_b64_tr_b16 v[86:87], v168 offset:0x1800
	ds_read_b64_tr_b16 v[88:89], v168 offset:0x2000
	ds_read_b64_tr_b16 v[90:91], v168 offset:0x2800
	ds_read_b64_tr_b16 v[92:93], v168 offset:0x3000
	ds_read_b64_tr_b16 v[94:95], v168 offset:0x3800
	s_waitcnt lgkmcnt(0)
	s_waitcnt vmcnt(0)
	v_mov_b32_e32 v162, v182
	v_mov_b32_e32 v163, v183
	v_mov_b32_e32 v172, v186
	v_mov_b32_e32 v173, v187
	v_mov_b32_e32 v182, v178
	v_mov_b32_e32 v183, v179
	v_mov_b32_e32 v190, v174
	v_mov_b32_e32 v191, v175
	ds_read_b64_tr_b16 v[96:97], v168 offset:0x200
	ds_read_b64_tr_b16 v[98:99], v168 offset:0xa00
	ds_read_b64_tr_b16 v[100:101], v168 offset:0x1200
	ds_read_b64_tr_b16 v[102:103], v168 offset:0x1a00
	ds_read_b64_tr_b16 v[104:105], v168 offset:0x2200
	ds_read_b64_tr_b16 v[106:107], v168 offset:0x2a00
	ds_read_b64_tr_b16 v[108:109], v168 offset:0x3200
	ds_read_b64_tr_b16 v[110:111], v168 offset:0x3a00
	s_waitcnt lgkmcnt(0)
	ds_read_b64_tr_b16 v[112:113], v168 offset:0x400
	ds_read_b64_tr_b16 v[114:115], v168 offset:0xc00
	ds_read_b64_tr_b16 v[116:117], v168 offset:0x1400
	ds_read_b64_tr_b16 v[118:119], v168 offset:0x1c00
	ds_read_b64_tr_b16 v[120:121], v168 offset:0x2400
	ds_read_b64_tr_b16 v[122:123], v168 offset:0x2c00
	ds_read_b64_tr_b16 v[124:125], v168 offset:0x3400
	ds_read_b64_tr_b16 v[126:127], v168 offset:0x3c00
	s_waitcnt lgkmcnt(0)
	ds_read_b64_tr_b16 v[152:153], v168 offset:0x600
	ds_read_b64_tr_b16 v[154:155], v168 offset:0xe00
	ds_read_b64_tr_b16 v[156:157], v168 offset:0x1600
	ds_read_b64_tr_b16 v[158:159], v168 offset:0x1e00
	ds_read_b64_tr_b16 v[164:165], v168 offset:0x2600
	ds_read_b64_tr_b16 v[166:167], v168 offset:0x2e00
	ds_read_b64_tr_b16 v[174:175], v168 offset:0x3600
	ds_read_b64_tr_b16 v[176:177], v168 offset:0x3e00
	s_waitcnt lgkmcnt(0)
	v_mfma_f32_16x16x32_bf16 v[64:67], v[160:163], v[148:151], v[64:67]
	v_cmp_eq_u32_e32 vcc, 0, v200
	v_mfma_f32_32x32x16_bf16 v[48:63], v[160:163], v[80:83], v[48:63]
	v_mfma_f32_32x32x16_bf16 v[32:47], v[160:163], v[96:99], v[32:47]
	v_mfma_f32_32x32x16_bf16 v[0:15], v[160:163], v[112:115], v[0:15]
	v_mfma_f32_32x32x16_bf16 v[16:31], v[160:163], v[152:155], v[16:31]
	v_mfma_f32_16x16x32_bf16 v[64:67], v[170:173], v[148:151], v[64:67]
	v_mfma_f32_32x32x16_bf16 v[48:63], v[170:173], v[84:87], v[48:63]
	v_mfma_f32_32x32x16_bf16 v[32:47], v[170:173], v[100:103], v[32:47]
	v_mfma_f32_32x32x16_bf16 v[0:15], v[170:173], v[116:119], v[0:15]
	v_mfma_f32_32x32x16_bf16 v[16:31], v[170:173], v[156:159], v[16:31]
	v_mfma_f32_16x16x32_bf16 v[64:67], v[180:183], v[148:151], v[64:67]
	v_mfma_f32_32x32x16_bf16 v[48:63], v[180:183], v[88:91], v[48:63]
	v_mfma_f32_32x32x16_bf16 v[32:47], v[180:183], v[104:107], v[32:47]
	v_mfma_f32_32x32x16_bf16 v[0:15], v[180:183], v[120:123], v[0:15]
	v_mfma_f32_32x32x16_bf16 v[16:31], v[180:183], v[164:167], v[16:31]
	v_mfma_f32_16x16x32_bf16 v[64:67], v[188:191], v[148:151], v[64:67]
	v_mfma_f32_32x32x16_bf16 v[48:63], v[188:191], v[92:95], v[48:63]
	v_mfma_f32_32x32x16_bf16 v[32:47], v[188:191], v[108:111], v[32:47]
	v_mfma_f32_32x32x16_bf16 v[0:15], v[188:191], v[124:127], v[0:15]
	v_mfma_f32_32x32x16_bf16 v[16:31], v[188:191], v[174:177], v[16:31]
	v_and_b32_e32 v248, 15, v200
	v_lshrrev_b32_e32 v249, 4, v200
	v_and_b32_e32 v250, 1, v200
	v_lshlrev_b32_e32 v249, 4, v249
	v_lshl_add_u32 v249, v250, 6, v249
	v_add_u32_e32 v249, s62, v249
	v_cmp_gt_u32_e64 s[98:99], 2, v248
	v_lshl_add_u32 v250, v198, 4, s62
	s_nop 7
	s_and_saveexec_b64 s[100:101], s[98:99]
	ds_write_b128 v249, v[64:67]
	s_mov_b64 exec, s[100:101]
	s_waitcnt lgkmcnt(0)
	ds_read_b128 v[64:67], v250
	ds_read_b128 v[68:71], v250 offset:32
	ds_read_b128 v[72:75], v250 offset:64
	ds_read_b128 v[76:79], v250 offset:96
	s_waitcnt lgkmcnt(0)
	s_and_saveexec_b64 s[6:7], vcc
	s_cbranch_execz .LBB0_108
	s_nop 5
	v_cmp_ngt_f32_e32 vcc, s85, v64
	v_cmp_ngt_f32_e64 s[4:5], s85, v65
	s_or_b64 s[4:5], vcc, s[4:5]
	v_cmp_ngt_f32_e32 vcc, s85, v66
	s_or_b64 s[4:5], s[4:5], vcc
	v_cmp_ngt_f32_e32 vcc, s85, v67
	s_or_b64 s[4:5], s[4:5], vcc
	v_cmp_ngt_f32_e32 vcc, s85, v68
	s_or_b64 s[4:5], s[4:5], vcc
	v_cmp_ngt_f32_e32 vcc, s85, v69
	s_or_b64 s[4:5], s[4:5], vcc
	v_cmp_ngt_f32_e32 vcc, s85, v70
	s_or_b64 s[4:5], s[4:5], vcc
	v_cmp_ngt_f32_e32 vcc, s85, v71
	s_or_b64 s[4:5], s[4:5], vcc
	v_cmp_ngt_f32_e32 vcc, s85, v72
	s_or_b64 s[4:5], s[4:5], vcc
	v_cmp_ngt_f32_e32 vcc, s85, v73
	s_or_b64 s[4:5], s[4:5], vcc
	v_cmp_ngt_f32_e32 vcc, s85, v74
	s_or_b64 s[4:5], s[4:5], vcc
	v_cmp_ngt_f32_e32 vcc, s85, v75
	s_or_b64 s[4:5], s[4:5], vcc
	v_cmp_ngt_f32_e32 vcc, s85, v76
	s_or_b64 s[4:5], s[4:5], vcc
	v_cmp_ngt_f32_e32 vcc, s85, v77
	s_or_b64 s[4:5], s[4:5], vcc
	v_cmp_ngt_f32_e32 vcc, s85, v78
	s_or_b64 s[4:5], s[4:5], vcc
	v_cmp_ngt_f32_e32 vcc, s85, v79
	s_or_b64 s[4:5], s[4:5], vcc
	v_cndmask_b32_e64 v80, 0, 1, s[4:5]
	v_cmp_ne_u32_e32 vcc, 0, v80
	s_cmp_lg_u64 vcc, 0
	s_cselect_b64 s[4:5], -1, 0
	v_cndmask_b32_e64 v80, 0, 1, s[4:5]
	v_readlane_b32 s4, v246, 17
	s_nop 1
	v_mov_b32_e32 v81, s4
	ds_write_b32 v81, v80

; #define SLOAD(i, k0) do { sr_[i].vs0 = *reinterpret_cast<const bf16x8*>(&Vh[(size_t)((k0) + sr) * LDQ + sc]); sr_[i].vs1 = *reinterpret_cast<const bf16x8*>(&Vh[(size_t)((k0) + 32 + sr) * LDQ + sc]); \
;     sr_[i].ks0 = *reinterpret_cast<const bf16x8*>(&Kh[(size_t)((k0) + sr) * LDQ + sc]); sr_[i].ks1 = *reinterpret_cast<const bf16x8*>(&Kh[(size_t)((k0) + 32 + sr) * LDQ + sc]); } while (0)
; #define SWRITE(b, i) do { *(bf16x8*)((char*)V_lds + (b) * SHM_V + vst0) = sr_[i].vs0;          \
;     *(bf16x8*)((char*)V_lds + (b) * SHM_V + vst1) = sr_[i].vs1; int kc = sc * 2;               \
;     *(bf16x8*)((char*)K_lds + (b) * SHM_K + KSWZ(sr, kc)) = sr_[i].ks0;                       \
;     *(bf16x8*)((char*)K_lds + (b) * SHM_K + KSWZ(32 + sr, kc)) = sr_[i].ks1; } while (0)
; template <bool SAFE>
; __device__ __forceinline__ void diff_core(const bf16* __restrict__ Kh, const bf16* __restrict__ Vh, const int NT, const bf16x8* qr, char* lds,
;                                           const int wid, const int lane_unused, f32x16* o, f32x16& lacc, float& l_reg) {
;     ...
;   const int kw0 = KSWZ(sr, sc * 2), kw1 = KSWZ(32 + sr, sc * 2);
;   SLOAD(0, 0); asm volatile("s_waitcnt vmcnt(0)" ::: "memory"); SWRITE(0, 0);
;   SLOAD(0, 64); asm volatile("s_waitcnt vmcnt(0)" ::: "memory"); SWRITE(1, 0); __syncthreads();
;   SLOAD(0, 128);
;   FIXUP(K_lds, true);
;   int bc = 1, bp = 0, bn = 2;
.LBB0_315:
	s_or_b64 exec, exec, s[6:7]
	v_and_b32_e32 v200, 63, v0
	v_lshlrev_b32_e32 v0, 4, v2
	v_and_b32_e32 v0, 0xc0, v0
	v_and_or_b32 v0, v1, 24, v0
	v_and_b32_e32 v2, 32, v4
	v_and_b32_e32 v1, 0x100, v1
	s_waitcnt lgkmcnt(0)
	v_add_u32_e32 v9, s62, v3
	v_or3_b32 v8, v0, v2, v1
	ds_read_b128 v[0:3], v9 offset:192
	ds_read_b128 v[4:7], v9 offset:224
	ds_read_b128 v[50:53], v9 offset:128
	ds_read_b128 v[54:57], v9 offset:160
	v_sub_f32_e32 v16, v16, v48
	v_sub_f32_e32 v17, v17, v48
	v_sub_f32_e32 v18, v18, v48
	v_sub_f32_e32 v19, v19, v48
	v_sub_f32_e32 v20, v20, v48
	v_sub_f32_e32 v21, v21, v48
	v_sub_f32_e32 v22, v22, v48
	v_sub_f32_e32 v23, v23, v48
	v_sub_f32_e32 v24, v24, v48
	v_sub_f32_e32 v25, v25, v48
	v_sub_f32_e32 v26, v26, v48
	v_sub_f32_e32 v27, v27, v48
	v_sub_f32_e32 v28, v28, v48
	v_sub_f32_e32 v29, v29, v48
	v_sub_f32_e32 v30, v30, v48
	v_sub_f32_e32 v31, v31, v48
	v_sub_f32_e32 v32, v32, v48
	v_sub_f32_e32 v33, v33, v48
	v_sub_f32_e32 v34, v34, v48
	v_sub_f32_e32 v35, v35, v48
	v_sub_f32_e32 v36, v36, v48
	v_sub_f32_e32 v37, v37, v48
	v_sub_f32_e32 v38, v38, v48
	v_sub_f32_e32 v39, v39, v48
	v_sub_f32_e32 v40, v40, v48
	v_sub_f32_e32 v41, v41, v48
	v_sub_f32_e32 v42, v42, v48
	v_sub_f32_e32 v43, v43, v48
	v_sub_f32_e32 v44, v44, v48
	v_sub_f32_e32 v45, v45, v48
	v_sub_f32_e32 v46, v46, v48
	v_sub_f32_e32 v47, v47, v48
	v_exp_f32_e32 v16, v16
	v_exp_f32_e32 v17, v17
	v_exp_f32_e32 v18, v18
	v_exp_f32_e32 v19, v19
	v_exp_f32_e32 v20, v20
	v_exp_f32_e32 v21, v21
	v_exp_f32_e32 v22, v22
	v_exp_f32_e32 v23, v23
	v_exp_f32_e32 v24, v24
	v_exp_f32_e32 v25, v25
	v_exp_f32_e32 v26, v26
	v_exp_f32_e32 v27, v27
	v_exp_f32_e32 v28, v28
	v_exp_f32_e32 v29, v29
	v_exp_f32_e32 v30, v30
	v_exp_f32_e32 v31, v31
	v_exp_f32_e32 v32, v32
	v_exp_f32_e32 v33, v33
	v_exp_f32_e32 v34, v34
	v_exp_f32_e32 v35, v35
	v_exp_f32_e32 v36, v36
	v_exp_f32_e32 v37, v37
	v_exp_f32_e32 v38, v38
	v_exp_f32_e32 v39, v39
	v_exp_f32_e32 v40, v40
	v_exp_f32_e32 v41, v41
	v_exp_f32_e32 v42, v42
	v_exp_f32_e32 v43, v43
	v_exp_f32_e32 v44, v44
	v_exp_f32_e32 v45, v45
	v_exp_f32_e32 v46, v46
	v_exp_f32_e32 v47, v47
	s_lshl_b32 s20, s26, 7
	s_cmp_lg_u32 0, -1
	s_cselect_b32 s7, 0, 0
	s_waitcnt lgkmcnt(2)
	v_pk_mul_f32 v[14:15], v[6:7], 0 op_sel_hi:[1,0]
	v_xor_b32_e32 v80, 0x80000000, v48
	v_add_u32_e32 v211, s7, v8
	v_pk_mul_f32 v[10:11], v[2:3], 0 op_sel_hi:[1,0]
	s_waitcnt lgkmcnt(0)
	v_pk_mul_f32 v[6:7], v[56:57], 0 op_sel_hi:[1,0]
	v_pk_mul_f32 v[2:3], v[52:53], 0 op_sel_hi:[1,0]
	v_pk_mul_f32 v[12:13], v[4:5], 0 op_sel_hi:[1,0]
	v_pk_mul_f32 v[8:9], v[0:1], 0 op_sel_hi:[1,0]
	v_pk_mul_f32 v[4:5], v[54:55], 0 op_sel_hi:[1,0]
	v_pk_mul_f32 v[0:1], v[50:51], 0 op_sel_hi:[1,0]
	v_cvt_pk_bf16_f32 v160, v16, v17
	v_cvt_pk_bf16_f32 v161, v18, v19
	v_cvt_pk_bf16_f32 v182, v20, v21
	v_cvt_pk_bf16_f32 v183, v22, v23
	v_cvt_pk_bf16_f32 v170, v24, v25
	v_cvt_pk_bf16_f32 v171, v26, v27
	v_cvt_pk_bf16_f32 v186, v28, v29
	v_cvt_pk_bf16_f32 v187, v30, v31
	v_cvt_pk_bf16_f32 v180, v32, v33
	v_cvt_pk_bf16_f32 v181, v34, v35
	v_cvt_pk_bf16_f32 v178, v36, v37
	v_cvt_pk_bf16_f32 v179, v38, v39
	v_cvt_pk_bf16_f32 v188, v40, v41
	v_cvt_pk_bf16_f32 v189, v42, v43
	v_cvt_pk_bf16_f32 v174, v44, v45
	v_cvt_pk_bf16_f32 v175, v46, v47
	v_mov_b32_e32 v64, 0
	v_mov_b64_e32 v[46:47], v[14:15]
	v_mov_b64_e32 v[62:63], v[14:15]
	v_mov_b64_e32 v[30:31], v[14:15]
	v_mov_b32_e32 v81, v80
	v_mov_b32_e32 v82, v80
	v_mov_b32_e32 v83, v80
	v_mov_b32_e32 v84, v80
	v_mov_b32_e32 v85, v80
	v_mov_b32_e32 v86, v80
	v_mov_b32_e32 v87, v80
	v_mov_b32_e32 v88, v80
	v_mov_b32_e32 v89, v80
	v_mov_b32_e32 v90, v80
	v_mov_b32_e32 v91, v80
	v_mov_b32_e32 v92, v80
	v_mov_b32_e32 v93, v80
	v_mov_b32_e32 v94, v80
	v_mov_b32_e32 v95, v80
	s_mov_b32 s6, 0
	s_mov_b32 s7, 1
	v_lshl_add_u64 v[190:191], s[14:15], 0, v[194:195]
	v_mad_u32_u24 v247, v201, s41, v194
	s_add_i32 s64, s55, -1
	s_mov_b32 s27, 2
	v_mov_b64_e32 v[44:45], v[12:13]
	v_mov_b64_e32 v[42:43], v[10:11]
	v_mov_b64_e32 v[40:41], v[8:9]
	v_mov_b64_e32 v[38:39], v[6:7]
	v_mov_b64_e32 v[36:37], v[4:5]
	v_mov_b64_e32 v[34:35], v[2:3]
	v_mov_b64_e32 v[32:33], v[0:1]
	v_mov_b64_e32 v[60:61], v[12:13]
	v_mov_b64_e32 v[58:59], v[10:11]
	v_mov_b64_e32 v[56:57], v[8:9]
	v_mov_b64_e32 v[54:55], v[6:7]
	v_mov_b64_e32 v[52:53], v[4:5]
	v_mov_b64_e32 v[50:51], v[2:3]
	v_mov_b64_e32 v[48:49], v[0:1]
	v_mov_b64_e32 v[28:29], v[12:13]
	v_mov_b64_e32 v[26:27], v[10:11]
	v_mov_b64_e32 v[24:25], v[8:9]
	v_mov_b64_e32 v[22:23], v[6:7]
	v_mov_b64_e32 v[20:21], v[4:5]
	v_mov_b64_e32 v[18:19], v[2:3]
	v_mov_b64_e32 v[16:17], v[0:1]
	s_mov_b32 s10, 1
	v_mov_b32_e32 v65, v64
	v_mov_b32_e32 v66, v64
	v_mov_b32_e32 v67, v64
	v_mov_b32_e32 v68, v64
	v_mov_b32_e32 v69, v64
	v_mov_b32_e32 v70, v64
	v_mov_b32_e32 v71, v64
	v_mov_b32_e32 v72, v64
	v_mov_b32_e32 v73, v64
	v_mov_b32_e32 v74, v64
	v_mov_b32_e32 v75, v64
	v_mov_b32_e32 v76, v64
	v_mov_b32_e32 v77, v64
	v_mov_b32_e32 v78, v64
	v_mov_b32_e32 v79, v64
	s_lshl_b32 s98, s10, 14
	v_add_u32_e32 v100, s98, v207
; template <int KS, bool SAFE> __device__ __forceinline__ void fused_ks(f32x16* o, f32x16& lacc, int vb, const VFrag& cur, VFrag& nxt, f32x16& p0, f32x16& p1, float& ps, ...
;   if constexpr (KS < 3) { vfrag_issue<KS + 1>(nxt, vb); asm volatile("s_waitcnt lgkmcnt(8)" ::: "memory"); }
;   else asm volatile("s_waitcnt lgkmcnt(0)" ::: "memory");
;   const bf16x8 pa = (KS == 0) ? pa0 : (KS == 1) ? pa1 : (KS == 2) ? pa2 : pa3;
;   SBAR();
;   o[0] = MFMA32(pa, PKV(cur.l0, cur.h0), o[0]); SBAR(); sm1_chunk<KS * 4 + 0>(p0, p1); if constexpr (KS > 0) SM2_UNIT(2 * KS - 1); SBAR();
;   o[1] = MFMA32(pa, PKV(cur.l1, cur.h1), o[1]); SBAR(); sm1_chunk<KS * 4 + 1>(p0, p1);
;   if (dow) {
;     if constexpr (KS == 0) { asm volatile("s_waitcnt vmcnt(0)" ::: "memory"); *reinterpret_cast<bf16x8*>(sd.k0) = st.ks0; }
;     else if constexpr (KS == 1) *reinterpret_cast<bf16x8*>(sd.k1) = st.ks1;
;     else if constexpr (KS == 2) *reinterpret_cast<bf16x8*>(sd.v0) = st.vs0;
;     else *reinterpret_cast<bf16x8*>(sd.v1) = st.vs1;
;   }
;   SBAR();
;   o[2] = MFMA32(pa, PKV(cur.l2, cur.h2), o[2]); SBAR(); sm1_chunk<KS * 4 + 2>(p0, p1); SM2_UNIT(2 * KS); SBAR();
;   o[3] = MFMA32(pa, PKV(cur.l3, cur.h3), o[3]); SBAR(); sm1_chunk<KS * 4 + 3>(p0, p1); SBAR();
;   if constexpr (!SAFE) { lacc = MFMA32(pa, ones, lacc); SBAR(); }
; }
; template <bool SAFE> ...
;   bf16x8 kb[8];
; #pragma unroll
;   for (int d0 = 0; d0 < 4; ++d0) { const int cb = (cb0 + d0 * 16 + hi * 8) * 2;
;     kb[2 * d0] = *reinterpret_cast<const bf16x8*>((const char*)Ks + KSWZ(r32, cb));
;     kb[2 * d0 + 1] = *reinterpret_cast<const bf16x8*>((const char*)Ks + KSWZ(32 + r32, cb)); }
;   VFrag fa, fb;
;   vfrag_issue<0>(fa, vb);
;   p0 = MFMA32(kb[0], qr[0], cinit); p1 = MFMA32(kb[1], qr[0], cinit);
; #pragma unroll
;   for (int d0 = 1; d0 < 4; ++d0) { p0 = MFMA32(kb[2 * d0], qr[d0], p0); p1 = MFMA32(kb[2 * d0 + 1], qr[d0], p1); }
;   SBAR();
;   unsigned a0, a1, b0, b1; ps = 0.f;
;   fused_ks<0, SAFE>(o, lacc, vb, fa, fb, p0, p1, ps, a0, a1, b0, b1, pa0, pa1, pa2, pa3, st, sd, dow, ones);
;   fused_ks<1, SAFE>(o, lacc, vb, fb, fa, p0, p1, ps, a0, a1, b0, b1, pa0, pa1, pa2, pa3, st, sd, dow, ones);
;   fused_ks<2, SAFE>(o, lacc, vb, fa, fb, p0, p1, ps, a0, a1, b0, b1, pa0, pa1, pa2, pa3, st, sd, dow, ones);
;   fused_ks<3, SAFE>(o, lacc, vb, fb, fa, p0, p1, ps, a0, a1, b0, b1, pa0, pa1, pa2, pa3, st, sd, dow, ones);
.LBB0_316:
	ds_read_b128 v[96:99], v100 offset:49152
	ds_read_b128 v[212:215], v100 offset:57344
	s_lshl_b32 s11, s10, 14
	s_add_i32 s8, s11, 0
	s_add_i32 s98, s7, 2
	s_min_i32 s98, s98, s64
	s_mul_i32 s98, s98, 0x60000
	s_add_u32 s98, s14, s98
	s_addc_u32 s99, s15, 0
	s_add_u32 s100, s98, 0x30000
	s_addc_u32 s101, s99, 0
	v_add_u32_e32 v172, s8, v208
	v_add_u32_e32 v173, s8, v209
	v_mov_b32_e32 v176, v180
	s_waitcnt lgkmcnt(1)
	v_mfma_f32_32x32x16_bf16 v[112:127], v[96:99], v[132:135], v[80:95]
	v_mov_b32_e32 v180, v160
	v_add_u32_e32 v160, s8, v210
	v_lshl_add_u32 v194, s6, 14, v211
	s_lshl_b32 s9, s27, 14
	s_add_i32 s9, s9, 0
	v_mov_b32_e32 v184, v170
	v_mov_b32_e32 v177, v181
	s_waitcnt lgkmcnt(0)
	v_mfma_f32_32x32x16_bf16 v[96:111], v[212:215], v[132:135], v[80:95]
	ds_read_b128 v[212:215], v172 offset:49152
	ds_read_b128 v[216:219], v172 offset:57344
	v_mov_b32_e32 v172, v188
	v_mov_b32_e32 v181, v161
	v_add_u32_e32 v188, s9, v205
	v_add_u32_e32 v161, s9, v203
	v_add_u32_e32 v170, s9, v204
	s_mov_b32 s26, s27
	s_waitcnt lgkmcnt(1)
	v_mfma_f32_32x32x16_bf16 v[112:127], v[212:215], v[136:139], v[112:127]
	ds_read_b128 v[212:215], v173 offset:49152
	v_mov_b32_e32 v185, v171
	s_waitcnt lgkmcnt(1)
	v_mfma_f32_32x32x16_bf16 v[96:111], v[216:219], v[136:139], v[96:111]
	ds_read_b128 v[216:219], v173 offset:57344
	v_mov_b32_e32 v173, v189
	v_add_u32_e32 v189, s9, v206
	s_waitcnt lgkmcnt(1)
	v_mfma_f32_32x32x16_bf16 v[112:127], v[212:215], v[140:143], v[112:127]
	ds_read_b128 v[212:215], v160 offset:49152
	s_waitcnt lgkmcnt(1)
	v_mfma_f32_32x32x16_bf16 v[96:111], v[216:219], v[140:143], v[96:111]
	ds_read_b128 v[216:219], v160 offset:57344
	ds_read_b64_tr_b16 v[220:221], v194 offset:0
	ds_read_b64_tr_b16 v[222:223], v194 offset:0x800
	s_waitcnt lgkmcnt(1)
	v_mfma_f32_32x32x16_bf16 v[112:127], v[212:215], v[144:147], v[112:127]
	ds_read_b64_tr_b16 v[212:213], v194 offset:0x200
	ds_read_b64_tr_b16 v[214:215], v194 offset:0xa00
	ds_read_b64_tr_b16 v[224:225], v194 offset:0x400
	ds_read_b64_tr_b16 v[226:227], v194 offset:0xc00
	ds_read_b64_tr_b16 v[228:229], v194 offset:0x600
	ds_read_b64_tr_b16 v[230:231], v194 offset:0xe00
	s_waitcnt lgkmcnt(0)
	v_mfma_f32_32x32x16_bf16 v[96:111], v[216:219], v[144:147], v[96:111]
	ds_read_b64_tr_b16 v[216:217], v194 offset:0x1000
	ds_read_b64_tr_b16 v[218:219], v194 offset:0x1800
	ds_read_b64_tr_b16 v[232:233], v194 offset:0x1200
	ds_read_b64_tr_b16 v[234:235], v194 offset:0x1a00
	ds_read_b64_tr_b16 v[236:237], v194 offset:0x1400
	ds_read_b64_tr_b16 v[238:239], v194 offset:0x1c00
	ds_read_b64_tr_b16 v[240:241], v194 offset:0x1600
	ds_read_b64_tr_b16 v[242:243], v194 offset:0x1e00
	s_waitcnt lgkmcnt(8)
	v_mfma_f32_32x32x16_bf16 v[48:63], v[180:183], v[220:223], v[48:63]
	s_nop 0
	v_exp_f32_e32 v112, v112
	v_exp_f32_e32 v113, v113
	v_mfma_f32_32x32x16_bf16 v[32:47], v[180:183], v[212:215], v[32:47]
	v_exp_f32_e32 v114, v114
	v_exp_f32_e32 v115, v115
	s_waitcnt vmcnt(3)
	ds_write_b128 v161, v[166:169] offset:49152
	global_load_dwordx4 v[166:169], v247, s[98:99] offset:1024
	v_mfma_f32_32x32x16_bf16 v[0:15], v[180:183], v[224:227], v[0:15]
	v_exp_f32_e32 v171, v116
	v_cvt_pk_bf16_f32 v160, v112, v113
	v_cvt_pk_bf16_f32 v161, v114, v115
	v_exp_f32_e32 v220, v117
	v_mfma_f32_32x32x16_bf16 v[16:31], v[180:183], v[228:231], v[16:31]
	v_exp_f32_e32 v221, v118
	v_exp_f32_e32 v222, v119
	v_mfma_f32_16x16x32_bf16 v[64:67], v[180:183], v[148:151], v[64:67]
	ds_read_b64_tr_b16 v[112:113], v194 offset:0x2000
	ds_read_b64_tr_b16 v[114:115], v194 offset:0x2800
	ds_read_b64_tr_b16 v[116:117], v194 offset:0x2200
	ds_read_b64_tr_b16 v[118:119], v194 offset:0x2a00
	ds_read_b64_tr_b16 v[248:249], v194 offset:0x2400
	ds_read_b64_tr_b16 v[250:251], v194 offset:0x2c00
	ds_read_b64_tr_b16 v[212:213], v194 offset:0x2600
	ds_read_b64_tr_b16 v[214:215], v194 offset:0x2e00
	s_waitcnt lgkmcnt(8)
	v_mfma_f32_32x32x16_bf16 v[48:63], v[184:187], v[216:219], v[48:63]
	v_cvt_pk_bf16_f32 v182, v171, v220
	v_cvt_pk_bf16_f32 v183, v221, v222
	v_exp_f32_e32 v120, v120
	v_exp_f32_e32 v121, v121
	v_mfma_f32_32x32x16_bf16 v[32:47], v[184:187], v[232:235], v[32:47]
	v_exp_f32_e32 v122, v122
	v_exp_f32_e32 v123, v123
	s_waitcnt vmcnt(3)
	ds_write_b128 v170, v[162:165] offset:49152
	global_load_dwordx4 v[162:165], v247, s[100:101] offset:1024
	v_mfma_f32_32x32x16_bf16 v[0:15], v[184:187], v[236:239], v[0:15]
	v_exp_f32_e32 v180, v124
	v_exp_f32_e32 v181, v125
	v_cvt_pk_bf16_f32 v170, v120, v121
	v_cvt_pk_bf16_f32 v171, v122, v123
	v_mfma_f32_32x32x16_bf16 v[16:31], v[184:187], v[240:243], v[16:31]
	v_exp_f32_e32 v220, v126
	v_exp_f32_e32 v221, v127
	v_mfma_f32_16x16x32_bf16 v[64:67], v[184:187], v[148:151], v[64:67]
	ds_read_b64_tr_b16 v[120:121], v194 offset:0x3000
	ds_read_b64_tr_b16 v[122:123], v194 offset:0x3800
	ds_read_b64_tr_b16 v[124:125], v194 offset:0x3200
	ds_read_b64_tr_b16 v[126:127], v194 offset:0x3a00
	ds_read_b64_tr_b16 v[252:253], v194 offset:0x3400
	ds_read_b64_tr_b16 v[254:255], v194 offset:0x3c00
	ds_read_b64_tr_b16 v[216:217], v194 offset:0x3600
	ds_read_b64_tr_b16 v[218:219], v194 offset:0x3e00
	s_waitcnt lgkmcnt(8)
	v_mfma_f32_32x32x16_bf16 v[48:63], v[176:179], v[112:115], v[48:63]
	v_cvt_pk_bf16_f32 v186, v180, v181
	v_cvt_pk_bf16_f32 v187, v220, v221
	v_exp_f32_e32 v96, v96
	v_exp_f32_e32 v97, v97
	v_mfma_f32_32x32x16_bf16 v[32:47], v[176:179], v[116:119], v[32:47]
	v_exp_f32_e32 v98, v98
	v_exp_f32_e32 v99, v99
	s_waitcnt vmcnt(3)
	ds_write_b128 v188, v[156:159]
	global_load_dwordx4 v[156:159], v247, s[98:99] offset:2048
	v_mfma_f32_32x32x16_bf16 v[0:15], v[176:179], v[248:251], v[0:15]
	v_cvt_pk_bf16_f32 v180, v96, v97
	v_cvt_pk_bf16_f32 v181, v98, v99
	v_exp_f32_e32 v100, v100
	v_exp_f32_e32 v101, v101
	v_mfma_f32_32x32x16_bf16 v[16:31], v[176:179], v[212:215], v[16:31]
	v_exp_f32_e32 v96, v102
	v_exp_f32_e32 v97, v103
	v_mfma_f32_16x16x32_bf16 v[64:67], v[176:179], v[148:151], v[64:67]
	s_waitcnt lgkmcnt(0)
	v_mfma_f32_32x32x16_bf16 v[48:63], v[172:175], v[120:123], v[48:63]
	v_cvt_pk_bf16_f32 v178, v100, v101
	v_cvt_pk_bf16_f32 v179, v96, v97
	v_exp_f32_e32 v98, v104
	v_exp_f32_e32 v99, v105
	v_mfma_f32_32x32x16_bf16 v[32:47], v[172:175], v[124:127], v[32:47]
	v_exp_f32_e32 v96, v106
	v_exp_f32_e32 v97, v107
	s_waitcnt vmcnt(3)
	ds_write_b128 v189, v[152:155]
	global_load_dwordx4 v[152:155], v247, s[100:101] offset:2048
	v_mfma_f32_32x32x16_bf16 v[0:15], v[172:175], v[252:255], v[0:15]
	v_cvt_pk_bf16_f32 v188, v98, v99
	v_cvt_pk_bf16_f32 v189, v96, v97
	v_exp_f32_e32 v100, v108
	v_exp_f32_e32 v101, v109
	v_mfma_f32_32x32x16_bf16 v[16:31], v[172:175], v[216:219], v[16:31]
	v_exp_f32_e32 v96, v110
	v_exp_f32_e32 v97, v111
	v_mfma_f32_16x16x32_bf16 v[64:67], v[172:175], v[148:151], v[64:67]
	v_cvt_pk_bf16_f32 v174, v100, v101
	v_cvt_pk_bf16_f32 v175, v96, v97
	s_add_i32 s7, s7, 1
	s_mov_b32 s27, s6
	s_mov_b32 s6, s10
	s_lshl_b32 s98, s26, 14
	v_add_u32_e32 v100, s98, v207
	s_cmp_lg_u32 s55, s7
	s_mov_b32 s10, s26
	s_waitcnt lgkmcnt(0)
	s_barrier
; #define MFMA32(a, b, c) __builtin_amdgcn_mfma_f32_32x32x16_bf16(a, b, c, 0, 0, 0)
; template <bool SAFE>
; __device__ __forceinline__ void diff_core(const bf16* __restrict__ Kh, const bf16* __restrict__ Vh, const int NT, const bf16x8* qr, char* lds,
;                                           const int wid, const int lane_unused, f32x16* o, f32x16& lacc, float& l_reg) {
;     ...
;   pv_d0(o, vb0 + bp * SHM_V, pa0, pa1, pa2, pa3);
;   if constexpr (!SAFE) {
;     lacc = MFMA32(pa0, ones, lacc); lacc = MFMA32(pa1, ones, lacc); lacc = MFMA32(pa2, ones, lacc); lacc = MFMA32(pa3, ones, lacc); }
; __device__ __forceinline__ void diff_attn_item(const bf16* __restrict__ qkv, bf16* __restrict__ mix, const float* __restrict__ dg,
;                                int tok0  , int key0  , int seq, int head, float lam, float oscale, const int W) {
;     ...
;     bool bad = (FORCE_SAFE != 0);
; #pragma unroll
;     for (int r = 0; r < 16; ++r) bad = bad || !(lacc[r] < 1.0e30f);
;     if (lane == 0) flag_l[wid] = __any(bad) ? 1 : 0;
	s_cbranch_scc1 .LBB0_316
	s_waitcnt vmcnt(0)
	v_add_u32_e32 v168, s11, v211
	ds_read_b64_tr_b16 v[80:81], v168 offset:0
	ds_read_b64_tr_b16 v[82:83], v168 offset:0x800
	ds_read_b64_tr_b16 v[84:85], v168 offset:0x1000
	ds_read_b64_tr_b16 v[86:87], v168 offset:0x1800
	ds_read_b64_tr_b16 v[88:89], v168 offset:0x2000
	ds_read_b64_tr_b16 v[90:91], v168 offset:0x2800
	ds_read_b64_tr_b16 v[92:93], v168 offset:0x3000
	ds_read_b64_tr_b16 v[94:95], v168 offset:0x3800
	s_waitcnt lgkmcnt(0)
	s_waitcnt vmcnt(0)
	v_mov_b32_e32 v162, v182
	v_mov_b32_e32 v163, v183
	v_mov_b32_e32 v172, v186
	v_mov_b32_e32 v173, v187
	v_mov_b32_e32 v182, v178
	v_mov_b32_e32 v183, v179
	v_mov_b32_e32 v190, v174
	v_mov_b32_e32 v191, v175
	ds_read_b64_tr_b16 v[96:97], v168 offset:0x200
	ds_read_b64_tr_b16 v[98:99], v168 offset:0xa00
	ds_read_b64_tr_b16 v[100:101], v168 offset:0x1200
	ds_read_b64_tr_b16 v[102:103], v168 offset:0x1a00
	ds_read_b64_tr_b16 v[104:105], v168 offset:0x2200
	ds_read_b64_tr_b16 v[106:107], v168 offset:0x2a00
	ds_read_b64_tr_b16 v[108:109], v168 offset:0x3200
	ds_read_b64_tr_b16 v[110:111], v168 offset:0x3a00
	s_waitcnt lgkmcnt(0)
	ds_read_b64_tr_b16 v[112:113], v168 offset:0x400
	ds_read_b64_tr_b16 v[114:115], v168 offset:0xc00
	ds_read_b64_tr_b16 v[116:117], v168 offset:0x1400
	ds_read_b64_tr_b16 v[118:119], v168 offset:0x1c00
	ds_read_b64_tr_b16 v[120:121], v168 offset:0x2400
	ds_read_b64_tr_b16 v[122:123], v168 offset:0x2c00
	ds_read_b64_tr_b16 v[124:125], v168 offset:0x3400
	ds_read_b64_tr_b16 v[126:127], v168 offset:0x3c00
	s_waitcnt lgkmcnt(0)
	ds_read_b64_tr_b16 v[152:153], v168 offset:0x600
	ds_read_b64_tr_b16 v[154:155], v168 offset:0xe00
	ds_read_b64_tr_b16 v[156:157], v168 offset:0x1600
	ds_read_b64_tr_b16 v[158:159], v168 offset:0x1e00
	ds_read_b64_tr_b16 v[164:165], v168 offset:0x2600
	ds_read_b64_tr_b16 v[166:167], v168 offset:0x2e00
	ds_read_b64_tr_b16 v[174:175], v168 offset:0x3600
	ds_read_b64_tr_b16 v[176:177], v168 offset:0x3e00
	s_waitcnt lgkmcnt(0)
	v_mfma_f32_16x16x32_bf16 v[64:67], v[160:163], v[148:151], v[64:67]
	v_cmp_eq_u32_e32 vcc, 0, v200
	v_mfma_f32_32x32x16_bf16 v[48:63], v[160:163], v[80:83], v[48:63]
	v_mfma_f32_32x32x16_bf16 v[32:47], v[160:163], v[96:99], v[32:47]
	v_mfma_f32_32x32x16_bf16 v[0:15], v[160:163], v[112:115], v[0:15]
	v_mfma_f32_32x32x16_bf16 v[16:31], v[160:163], v[152:155], v[16:31]
	v_mfma_f32_16x16x32_bf16 v[64:67], v[170:173], v[148:151], v[64:67]
	v_mfma_f32_32x32x16_bf16 v[48:63], v[170:173], v[84:87], v[48:63]
	v_mfma_f32_32x32x16_bf16 v[32:47], v[170:173], v[100:103], v[32:47]
	v_mfma_f32_32x32x16_bf16 v[0:15], v[170:173], v[116:119], v[0:15]
	v_mfma_f32_32x32x16_bf16 v[16:31], v[170:173], v[156:159], v[16:31]
	v_mfma_f32_16x16x32_bf16 v[64:67], v[180:183], v[148:151], v[64:67]
	v_mfma_f32_32x32x16_bf16 v[48:63], v[180:183], v[88:91], v[48:63]
	v_mfma_f32_32x32x16_bf16 v[32:47], v[180:183], v[104:107], v[32:47]
	v_mfma_f32_32x32x16_bf16 v[0:15], v[180:183], v[120:123], v[0:15]
	v_mfma_f32_32x32x16_bf16 v[16:31], v[180:183], v[164:167], v[16:31]
	v_mfma_f32_16x16x32_bf16 v[64:67], v[188:191], v[148:151], v[64:67]
	v_mfma_f32_32x32x16_bf16 v[48:63], v[188:191], v[92:95], v[48:63]
	v_mfma_f32_32x32x16_bf16 v[32:47], v[188:191], v[108:111], v[32:47]
	v_mfma_f32_32x32x16_bf16 v[0:15], v[188:191], v[124:127], v[0:15]
	v_mfma_f32_32x32x16_bf16 v[16:31], v[188:191], v[174:177], v[16:31]
	v_and_b32_e32 v248, 15, v200
	v_lshrrev_b32_e32 v249, 4, v200
	v_and_b32_e32 v250, 1, v200
	v_lshlrev_b32_e32 v249, 4, v249
	v_lshl_add_u32 v249, v250, 6, v249
	v_add_u32_e32 v249, s62, v249
	v_cmp_gt_u32_e64 s[98:99], 2, v248
	v_lshl_add_u32 v250, v198, 4, s62
	s_nop 7
	s_and_saveexec_b64 s[100:101], s[98:99]
	ds_write_b128 v249, v[64:67]
	s_mov_b64 exec, s[100:101]
	s_waitcnt lgkmcnt(0)
	ds_read_b128 v[64:67], v250
	ds_read_b128 v[68:71], v250 offset:32
	ds_read_b128 v[72:75], v250 offset:64
	ds_read_b128 v[76:79], v250 offset:96
	s_waitcnt lgkmcnt(0)
	s_and_saveexec_b64 s[10:11], vcc
	s_cbranch_execz .LBB0_319
	s_nop 5
	v_cmp_ngt_f32_e32 vcc, s44, v64
	v_cmp_ngt_f32_e64 s[6:7], s44, v65
	s_or_b64 s[6:7], vcc, s[6:7]
	v_cmp_ngt_f32_e32 vcc, s44, v66
	s_or_b64 s[6:7], s[6:7], vcc
	v_cmp_ngt_f32_e32 vcc, s44, v67
	s_or_b64 s[6:7], s[6:7], vcc
	v_cmp_ngt_f32_e32 vcc, s44, v68
	s_or_b64 s[6:7], s[6:7], vcc
	v_cmp_ngt_f32_e32 vcc, s44, v69
	s_or_b64 s[6:7], s[6:7], vcc
	v_cmp_ngt_f32_e32 vcc, s44, v70
	s_or_b64 s[6:7], s[6:7], vcc
	v_cmp_ngt_f32_e32 vcc, s44, v71
	s_or_b64 s[6:7], s[6:7], vcc
	v_cmp_ngt_f32_e32 vcc, s44, v72
	s_or_b64 s[6:7], s[6:7], vcc
	v_cmp_ngt_f32_e32 vcc, s44, v73
	s_or_b64 s[6:7], s[6:7], vcc
	v_cmp_ngt_f32_e32 vcc, s44, v74
	s_or_b64 s[6:7], s[6:7], vcc
	v_cmp_ngt_f32_e32 vcc, s44, v75
	s_or_b64 s[6:7], s[6:7], vcc
	v_cmp_ngt_f32_e32 vcc, s44, v76
	s_or_b64 s[6:7], s[6:7], vcc
	v_cmp_ngt_f32_e32 vcc, s44, v77
	s_or_b64 s[6:7], s[6:7], vcc
	v_cmp_ngt_f32_e32 vcc, s44, v78
	s_or_b64 s[6:7], s[6:7], vcc
	v_cmp_ngt_f32_e32 vcc, s44, v79
	s_or_b64 s[6:7], s[6:7], vcc
	v_cndmask_b32_e64 v80, 0, 1, s[6:7]
	v_cmp_ne_u32_e32 vcc, 0, v80
	s_cmp_lg_u64 vcc, 0
	s_cselect_b64 s[6:7], -1, 0
	v_cndmask_b32_e64 v80, 0, 1, s[6:7]
	v_readlane_b32 s6, v246, 17
	s_nop 1
	v_mov_b32_e32 v81, s6
	ds_write_b32 v81, v80
